# v35 + FoX tile loop: LDS write addresses and K/F global address math hoisted / strength-reduced (14 VALU fewer per tile)
# speedup vs baseline: 1.0059x; 1.0051x over previous
; template <int DK, int MODE> ...
;     ...
;   f32x16 o0, o1;
; #pragma unroll
;   for (int e = 0; e < 16; ++e) { o0[e] = 0.f; o1[e] = 0.f; }
;   float m = -1e30f, lsum = 0.f, R = 1.f;
;   u32x4 rk[NKL], rv[2];
;   float rf = 0.f;
;   auto gload = [&](int jt) {
; #pragma unroll
;     for (int i = 0; i < NKL; ++i) {
;       const int id = tid + 256 * i, row = id / KCH, ch = id % KCH;
;       rk[i] = *(const u32x4*)(K + (size_t)(jt * 64 + row) * DK + ch * 8);
;     }
; #pragma unroll
;     for (int i = 0; i < 2; ++i) {
;       const int id = tid + 256 * i, row = id >> 3, ch = id & 7;
;       rv[i] = *(const u32x4*)(Vt + (size_t)row * Skv + jt * 64 + ch * 8);
;     }
;     if (MODE == 1) rf = F[jt * 64 + (tid & 63)];
;   };
;   auto swrite = [&](int buf) {
; #pragma unroll
;     for (int i = 0; i < NKL; ++i) {
;       const int id = tid + 256 * i, row = id / KCH, ch = id % KCH;
;       *(u32x4*)(sK + buf * 64 * LDK + row * LDK + ch * 8) = rk[i];
;     }
; #pragma unroll
;     for (int i = 0; i < 2; ++i) {
;       const int id = tid + 256 * i, row = id >> 3, ch = id & 7;
;       *(u32x4*)(sV + buf * 64 * 72 + row * 72 + ch * 8) = rv[i];
;     }
;     if (MODE == 1) { if (tid < 64) sF[buf * 64 + tid] = Fref - rf; }
;   };
.LBB0_556:
	s_andn2_b64 vcc, exec, s[22:23]
	s_cbranch_vccnz .LBB0_571
	v_lshlrev_b32_e32 v2, 3, v9
	v_mul_u32_u24_e32 v3, 0x48, v8
	v_lshlrev_b32_e32 v2, 1, v2
	v_mov_b32_e32 v18, v1
	v_mov_b32_e32 v19, v1
	v_lshl_add_u64 v[140:141], v[136:137], 1, s[10:11]
	v_lshl_add_u64 v[142:143], v[4:5], 0, v[0:1]
	v_lshl_add_u64 v[152:153], v[6:7], 0, v[0:1]
	v_lshl_add_u32 v137, v3, 1, v2
	v_mov_b32_e32 v20, v1
	v_mov_b32_e32 v21, v1
	v_mov_b32_e32 v22, v1
	v_mov_b32_e32 v23, v1
	v_mov_b32_e32 v24, v1
	v_mov_b32_e32 v25, v1
	v_mov_b32_e32 v26, v1
	v_mov_b32_e32 v27, v1
	v_mov_b32_e32 v28, v1
	v_mov_b32_e32 v29, v1
	v_mov_b32_e32 v30, v1
	v_mov_b32_e32 v31, v1
	v_mov_b32_e32 v32, v1
	v_mov_b32_e32 v33, v1
	v_mov_b64_e32 v[2:3], v[18:19]
	s_mov_b32 s2, 1
	v_lshl_add_u64 v[138:139], v[134:135], 1, s[10:11]
	s_or_b32 s12, s1, 31
	s_add_i32 s10, s20, 64
	v_mov_b32_e32 v163, 0xf149f2ca
	v_mov_b32_e32 v135, 0
	v_mov_b64_e32 v[4:5], v[20:21]
	v_mov_b64_e32 v[6:7], v[22:23]
	v_mov_b64_e32 v[8:9], v[24:25]
	v_mov_b64_e32 v[10:11], v[26:27]
	v_mov_b64_e32 v[12:13], v[28:29]
	v_mov_b64_e32 v[14:15], v[30:31]
	v_mov_b64_e32 v[16:17], v[32:33]
	v_lshlrev_b32_e32 v222, 1, v156
	v_lshl_add_u32 v222, v134, 1, v222
	v_lshlrev_b32_e32 v223, 1, v157
	v_lshl_add_u32 v223, v136, 1, v223
	v_lshl_add_u32 v224, v158, 1, v0
	v_lshl_add_u32 v225, v159, 1, v0
	v_lshlrev_b32_e32 v226, 7, v154
	v_mov_b32_e32 v227, 0
	v_lshl_add_u64 v[228:229], v[138:139], 0, v[226:227]
	v_lshlrev_b32_e32 v226, 7, v155
	v_lshl_add_u64 v[230:231], v[140:141], 0, v[226:227]
	v_lshlrev_b32_e32 v226, 2, v149
	v_lshl_add_u64 v[232:233], s[8:9], 0, v[226:227]
	s_branch .LBB0_560

; template <int DK, int MODE> ...
;     ...
;   auto gload = [&](int jt) {
; #pragma unroll
;     for (int i = 0; i < NKL; ++i) {
;       const int id = tid + 256 * i, row = id / KCH, ch = id % KCH;
;       rk[i] = *(const u32x4*)(K + (size_t)(jt * 64 + row) * DK + ch * 8);
;     }
; #pragma unroll
;     for (int i = 0; i < 2; ++i) {
;       const int id = tid + 256 * i, row = id >> 3, ch = id & 7;
;       rv[i] = *(const u32x4*)(Vt + (size_t)row * Skv + jt * 64 + ch * 8);
;     }
;     if (MODE == 1) rf = F[jt * 64 + (tid & 63)];
;   };
.LBB0_560:
	s_cmp_lt_i32 s2, s0
	s_cselect_b64 s[22:23], -1, 0
	s_cmp_ge_i32 s2, s0
	s_cselect_b64 s[20:21], -1, 0
	s_and_b64 vcc, exec, s[20:21]
	s_cbranch_vccnz .LBB0_562
	s_ashr_i32 s11, s10, 31
	s_lshl_b64 s[24:25], s[10:11], 1
	s_lshl_b64 s[100:101], s[10:11], 7
	v_lshl_add_u64 v[34:35], v[228:229], 0, s[100:101]
	v_lshl_add_u64 v[36:37], v[230:231], 0, s[100:101]
	global_load_dwordx4 v[82:85], v[34:35], off
	global_load_dwordx4 v[86:89], v[36:37], off
	v_lshl_add_u64 v[34:35], v[142:143], 0, s[24:25]
	v_lshl_add_u64 v[36:37], v[152:153], 0, s[24:25]
	global_load_dwordx4 v[90:93], v[34:35], off
	global_load_dwordx4 v[94:97], v[36:37], off
	v_lshl_add_u64 v[34:35], s[24:25], 1, v[232:233]
	global_load_dword v160, v[34:35], off

; template <int DK, int MODE> ...
;     ...
;   auto swrite = [&](int buf) {
; #pragma unroll
;     for (int i = 0; i < NKL; ++i) {
;       const int id = tid + 256 * i, row = id / KCH, ch = id % KCH;
;       *(u32x4*)(sK + buf * 64 * LDK + row * LDK + ch * 8) = rk[i];
;     }
; #pragma unroll
;     for (int i = 0; i < 2; ++i) {
;       const int id = tid + 256 * i, row = id >> 3, ch = id & 7;
;       *(u32x4*)(sV + buf * 64 * 72 + row * 72 + ch * 8) = rv[i];
;     }
;     if (MODE == 1) { if (tid < 64) sF[buf * 64 + tid] = Fref - rf; }
;   };
.LBB0_568:
	s_andn2_b64 vcc, exec, s[22:23]
	s_cbranch_vccnz .LBB0_559
	s_xor_b32 s11, s11, 1
	s_mul_i32 s13, s11, 0x2400
	v_add_u32_e32 v34, s13, v222
	s_waitcnt vmcnt(4)
	ds_write_b128 v34, v[82:85]
	v_add_u32_e32 v34, s13, v223
	s_waitcnt vmcnt(3)
	ds_write_b128 v34, v[86:89]
	v_add_u32_e32 v34, s13, v224
	s_waitcnt vmcnt(2)
	ds_write_b128 v34, v[90:93] offset:18432
	v_add_u32_e32 v34, s13, v225
	s_waitcnt vmcnt(1)
	ds_write_b128 v34, v[94:97] offset:18432
	s_and_saveexec_b64 s[22:23], s[38:39]
	s_cbranch_execz .LBB0_558
	v_lshl_add_u32 v34, s11, 8, v161
	s_waitcnt vmcnt(0)
	v_sub_f32_e32 v35, v133, v160
	ds_write_b32 v34, v35 offset:36864
	s_branch .LBB0_558
